# code placement: P3 attention tile loops, scan chunk loops and the P8 exchange spin loop also pinned to 64-byte boundaries
# baseline (speedup 1.0000x reference)
.LBB0_808:
	v_readfirstlane_b32 s6, v243
	s_lshr_b32 s47, s6, 8
	s_sub_i32 s24, s46, s36
	s_lshl_b32 s25, s47, 6
	s_add_i32 s4, s25, s24
	s_ashr_i32 s5, s4, 31
	s_lshr_b32 s46, s6, 6
	s_lshl_b64 s[22:23], s[4:5], 2
	s_add_u32 s22, s18, s22
	v_lshl_or_b32 v4, s4, 6, v140
	s_addc_u32 s23, s19, s23
	v_ashrrev_i32_e32 v5, 31, v4
	global_load_dword v40, v143, s[22:23]
	v_lshlrev_b64 v[0:1], 2, v[4:5]
	v_lshl_add_u64 v[8:9], s[16:17], 0, v[0:1]
	v_lshl_add_u64 v[6:7], s[14:15], 0, v[0:1]
	global_load_dword v3, v[8:9], off
	global_load_dword v2, v[6:7], off
	global_load_dword v0, v[6:7], off offset:128
	global_load_dword v1, v[8:9], off offset:128
	v_lshl_or_b32 v6, s4, 4, v150
	v_or_b32_e32 v8, 32, v4
	v_ashrrev_i32_e32 v7, 31, v6
	v_ashrrev_i32_e32 v9, 31, v8
	v_lshlrev_b64 v[4:5], 6, v[4:5]
	v_lshlrev_b64 v[6:7], 8, v[6:7]
	v_lshl_add_u64 v[10:11], v[146:147], 0, v[4:5]
	v_lshl_add_u64 v[16:17], v[148:149], 0, v[4:5]
	v_lshlrev_b64 v[4:5], 6, v[8:9]
	v_lshl_add_u64 v[36:37], v[160:161], 0, v[6:7]
	v_lshl_add_u64 v[24:25], v[146:147], 0, v[4:5]
	v_lshl_add_u64 v[32:33], v[148:149], 0, v[4:5]
	v_lshl_add_u64 v[38:39], v[162:163], 0, v[6:7]
	global_load_dwordx4 v[4:7], v[10:11], off offset:16
	s_nop 0
	global_load_dwordx4 v[8:11], v[10:11], off
	s_nop 0
	global_load_dwordx4 v[12:15], v[16:17], off offset:16
	s_nop 0
	global_load_dwordx4 v[16:19], v[16:17], off
	s_nop 0
	global_load_dwordx4 v[20:23], v[24:25], off offset:16
	s_nop 0
	global_load_dwordx4 v[24:27], v[24:25], off
	s_nop 0
	global_load_dwordx4 v[28:31], v[32:33], off offset:16
	s_nop 0
	global_load_dwordx4 v[32:35], v[32:33], off
	s_nop 0
	global_load_dwordx2 v[136:137], v[36:37], off
	global_load_dwordx2 v[126:127], v[36:37], off offset:16
	global_load_dwordx2 v[116:117], v[36:37], off offset:32
	global_load_dwordx2 v[190:191], v[36:37], off offset:48
	global_load_dwordx2 v[184:185], v[36:37], off offset:128
	global_load_dwordx2 v[138:139], v[36:37], off offset:144
	global_load_dwordx2 v[122:123], v[36:37], off offset:160
	global_load_dwordx2 v[192:193], v[36:37], off offset:176
	global_load_dwordx2 v[186:187], v[38:39], off
	global_load_dwordx2 v[176:177], v[38:39], off offset:16
	global_load_dwordx2 v[128:129], v[38:39], off offset:32
	global_load_dwordx2 v[194:195], v[38:39], off offset:48
	global_load_dwordx2 v[188:189], v[38:39], off offset:128
	global_load_dwordx2 v[180:181], v[38:39], off offset:144
	global_load_dwordx2 v[132:133], v[38:39], off offset:160
	global_load_dwordx2 v[196:197], v[38:39], off offset:176
	global_load_dwordx2 v[120:121], v[36:37], off offset:64
	global_load_dwordx2 v[112:113], v[36:37], off offset:80
	global_load_dwordx2 v[108:109], v[36:37], off offset:96
	global_load_dwordx2 v[198:199], v[36:37], off offset:112
	global_load_dwordx2 v[174:175], v[36:37], off offset:192
	global_load_dwordx2 v[124:125], v[36:37], off offset:208
	global_load_dwordx2 v[110:111], v[36:37], off offset:224
	global_load_dwordx2 v[200:201], v[36:37], off offset:240
	global_load_dwordx2 v[178:179], v[38:39], off offset:64
	global_load_dwordx2 v[130:131], v[38:39], off offset:80
	global_load_dwordx2 v[114:115], v[38:39], off offset:96
	global_load_dwordx2 v[202:203], v[38:39], off offset:112
	global_load_dwordx2 v[182:183], v[38:39], off offset:192
	global_load_dwordx2 v[134:135], v[38:39], off offset:208
	global_load_dwordx2 v[118:119], v[38:39], off offset:224
	global_load_dwordx2 v[204:205], v[38:39], off offset:240
	s_bfe_u32 s34, s6, 0x20006
	s_lshl_b32 s20, s34, 8
	s_lshl_b32 s22, s24, 4
	s_ashr_i32 s23, s22, 31
	s_cmpk_lt_u32 s6, 0x100
	s_mov_b32 s26, s21
	v_mov_b32_e32 v206, v143
	v_mov_b32_e32 v207, v143
	v_mov_b32_e32 v208, v143
	v_mov_b32_e32 v209, v143
	s_waitcnt vmcnt(0)
	v_mul_f32_e32 v46, 0x3fb8aa3b, v40
	v_exp_f32_e32 v46, v46
	v_pk_mul_f32 v[40:41], v[2:3], v[2:3]
	v_mov_b32_e32 v42, v3
	v_add_f32_e32 v48, v40, v41
	v_div_scale_f32 v50, s[4:5], v48, v48, 1.0
	v_rcp_f32_e32 v54, v50
	v_pk_mul_f32 v[44:45], v[0:1], v[0:1]
	v_mul_f32_e32 v40, v2, v46
	v_add_f32_e32 v49, v44, v45
	v_mul_f32_e32 v44, v46, v3
	v_mul_f32_e32 v45, v46, v1
	v_mul_f32_e32 v41, v46, v0
	v_mul_f32_e32 v46, 0.15915494, v44
	v_mul_f32_e32 v47, 0.15915494, v45
	v_div_scale_f32 v52, s[4:5], v49, v49, 1.0
	v_rndne_f32_e32 v46, v46
	v_fma_f32 v56, -v50, v54, 1.0
	v_rndne_f32_e32 v47, v47
	v_div_scale_f32 v51, vcc, 1.0, v48, 1.0
	v_rcp_f32_e32 v55, v52
	v_fmac_f32_e32 v44, 0xc0c90fdb, v46
	v_fmac_f32_e32 v54, v56, v54
	v_fmac_f32_e32 v45, 0xc0c90fdb, v47
	v_fmac_f32_e32 v44, 0x343bbd2e, v46
	v_mul_f32_e32 v56, v51, v54
	v_fmac_f32_e32 v45, 0x343bbd2e, v47
	v_mul_f32_e32 v40, 0x3fb8aa3b, v40
	v_mul_f32_e32 v41, 0x3fb8aa3b, v41
	v_mul_f32_e32 v46, 0.15915494, v44
	v_fma_f32 v47, -v50, v56, v51
	v_mul_f32_e32 v58, 0.15915494, v45
	v_exp_f32_e32 v40, v40
	v_exp_f32_e32 v41, v41
	v_sin_f32_e32 v44, v46
	v_cos_f32_e32 v46, v46
	v_fmac_f32_e32 v56, v47, v54
	v_sin_f32_e32 v45, v58
	v_cos_f32_e32 v47, v58
	v_fma_f32 v57, -v52, v55, 1.0
	v_div_scale_f32 v53, s[4:5], 1.0, v49, 1.0
	v_fmac_f32_e32 v55, v57, v55
	v_mul_f32_e32 v57, v53, v55
	v_fma_f32 v59, -v52, v57, v53
	v_pk_mul_f32 v[168:169], v[40:41], v[46:47]
	v_pk_mul_f32 v[170:171], v[40:41], v[44:45]
	v_mov_b32_e32 v43, v2
	v_fmac_f32_e32 v57, v59, v55
	v_fma_f32 v50, -v50, v56, v51
	v_add_f32_e32 v41, -1.0, v168
	v_mov_b32_e32 v40, v170
	v_fma_f32 v51, -v52, v57, v53
	v_div_fmas_f32 v50, v50, v54, v56
	s_mov_b64 vcc, s[4:5]
	v_pk_mul_f32 v[42:43], v[42:43], v[40:41]
	v_pk_mul_f32 v[2:3], v[2:3], v[40:41]
	v_div_fixup_f32 v48, v50, v48, 1.0
	v_div_fmas_f32 v50, v51, v55, v57
	v_add_f32_e32 v40, v42, v43
	v_sub_f32_e32 v3, v2, v3
	v_mul_f32_e32 v2, v48, v40
	v_mul_f32_e32 v40, v48, v3
	v_div_fixup_f32 v3, v50, v49, 1.0
	v_add_f32_e32 v37, -1.0, v169
	v_mov_b32_e32 v38, v1
	v_mov_b32_e32 v39, v0
	v_mov_b32_e32 v36, v171
	v_pk_mul_f32 v[38:39], v[38:39], v[36:37]
	v_pk_mul_f32 v[0:1], v[0:1], v[36:37]
	v_pk_mul_f32 v[36:37], v[16:17], v[40:41] op_sel_hi:[1,0]
	v_pk_mul_f32 v[16:17], v[16:17], v[2:3] op_sel_hi:[1,0]
	v_pk_fma_f32 v[36:37], v[8:9], v[2:3], v[36:37] op_sel_hi:[1,0,1] neg_lo:[0,0,1] neg_hi:[0,0,1]
	v_pk_fma_f32 v[8:9], v[8:9], v[40:41], v[16:17] op_sel_hi:[1,0,1]
	v_pk_mul_f32 v[16:17], v[18:19], v[40:41] op_sel_hi:[1,0]
	v_add_f32_e32 v38, v38, v39
	v_pk_fma_f32 v[16:17], v[10:11], v[2:3], v[16:17] op_sel_hi:[1,0,1] neg_lo:[0,0,1] neg_hi:[0,0,1]
	v_sub_f32_e32 v0, v0, v1
	v_cvt_pk_bf16_f32 v65, v16, v17
	v_pk_mul_f32 v[16:17], v[18:19], v[2:3] op_sel_hi:[1,0]
	v_mul_f32_e32 v38, v3, v38
	v_pk_fma_f32 v[10:11], v[10:11], v[40:41], v[16:17] op_sel_hi:[1,0,1]
	v_pk_mul_f32 v[16:17], v[40:41], v[12:13] op_sel_hi:[0,1]
	v_pk_mul_f32 v[12:13], v[2:3], v[12:13] op_sel_hi:[0,1]
	v_pk_fma_f32 v[16:17], v[2:3], v[4:5], v[16:17] op_sel_hi:[0,1,1] neg_lo:[0,0,1] neg_hi:[0,0,1]
	v_pk_fma_f32 v[4:5], v[40:41], v[4:5], v[12:13] op_sel_hi:[0,1,1]
	v_pk_mul_f32 v[12:13], v[40:41], v[14:15] op_sel_hi:[0,1]
	v_mul_f32_e32 v0, v3, v0
	v_pk_fma_f32 v[12:13], v[2:3], v[6:7], v[12:13] op_sel_hi:[0,1,1] neg_lo:[0,0,1] neg_hi:[0,0,1]
	v_pk_mul_f32 v[2:3], v[2:3], v[14:15] op_sel_hi:[0,1]
	v_pk_fma_f32 v[2:3], v[40:41], v[6:7], v[2:3] op_sel_hi:[0,1,1]
	v_cvt_pk_bf16_f32 v68, v8, v9
	v_cvt_pk_bf16_f32 v70, v4, v5
	v_cvt_pk_bf16_f32 v71, v2, v3
	v_pk_mul_f32 v[2:3], v[0:1], v[32:33] op_sel_hi:[0,1]
	v_pk_mul_f32 v[4:5], v[0:1], v[34:35] op_sel_hi:[0,1]
	v_pk_mul_f32 v[6:7], v[0:1], v[28:29] op_sel_hi:[0,1]
	v_pk_mul_f32 v[8:9], v[0:1], v[30:31] op_sel_hi:[0,1]
	v_pk_fma_f32 v[2:3], v[38:39], v[24:25], v[2:3] op_sel_hi:[0,1,1] neg_lo:[0,0,1] neg_hi:[0,0,1]
	v_pk_fma_f32 v[4:5], v[38:39], v[26:27], v[4:5] op_sel_hi:[0,1,1] neg_lo:[0,0,1] neg_hi:[0,0,1]
	v_pk_fma_f32 v[6:7], v[38:39], v[20:21], v[6:7] op_sel_hi:[0,1,1] neg_lo:[0,0,1] neg_hi:[0,0,1]
	v_pk_fma_f32 v[8:9], v[38:39], v[22:23], v[8:9] op_sel_hi:[0,1,1] neg_lo:[0,0,1] neg_hi:[0,0,1]
	v_cvt_pk_bf16_f32 v72, v2, v3
	v_pk_mul_f32 v[2:3], v[38:39], v[32:33] op_sel_hi:[0,1]
	v_cvt_pk_bf16_f32 v73, v4, v5
	v_pk_mul_f32 v[4:5], v[38:39], v[34:35] op_sel_hi:[0,1]
	v_cvt_pk_bf16_f32 v74, v6, v7
	v_pk_mul_f32 v[6:7], v[38:39], v[28:29] op_sel_hi:[0,1]
	v_cvt_pk_bf16_f32 v75, v8, v9
	v_pk_mul_f32 v[8:9], v[38:39], v[30:31] op_sel_hi:[0,1]
	v_pk_fma_f32 v[2:3], v[0:1], v[24:25], v[2:3] op_sel_hi:[0,1,1]
	v_pk_fma_f32 v[4:5], v[0:1], v[26:27], v[4:5] op_sel_hi:[0,1,1]
	v_pk_fma_f32 v[6:7], v[0:1], v[20:21], v[6:7] op_sel_hi:[0,1,1]
	v_pk_fma_f32 v[0:1], v[0:1], v[22:23], v[8:9] op_sel_hi:[0,1,1]
	v_cvt_pk_bf16_f32 v79, v0, v1
	v_or_b32_e32 v0, s20, v212
	v_lshlrev_b32_e32 v142, 11, v0
	v_lshl_add_u64 v[0:1], s[12:13], 0, v[142:143]
	v_lshl_add_u64 v[0:1], s[22:23], 1, v[0:1]
	v_lshl_add_u64 v[0:1], v[0:1], 0, v[164:165]
	s_mov_b64 s[4:5], 0x1000000
	v_lshl_add_u64 v[172:173], v[0:1], 0, s[4:5]
	s_cselect_b64 s[4:5], -1, 0
	s_cmpk_gt_u32 s6, 0xff
	v_cvt_pk_bf16_f32 v64, v36, v37
	v_cvt_pk_bf16_f32 v66, v16, v17
	v_cvt_pk_bf16_f32 v67, v12, v13
	v_cvt_pk_bf16_f32 v69, v10, v11
	v_cvt_pk_bf16_f32 v76, v2, v3
	v_cvt_pk_bf16_f32 v77, v4, v5
	v_cvt_pk_bf16_f32 v78, v6, v7
	s_cselect_b64 s[28:29], -1, 0
	s_mov_b64 s[6:7], -1
	s_nop 0
	s_nop 0
	s_nop 0
	s_nop 0
	s_nop 0

.LBB0_826:
	v_cndmask_b32_e64 v2, 0, v190, s[0:1]
	v_cndmask_b32_e64 v3, 0, v192, s[0:1]
	v_cvt_pk_bf16_f32 v80, v2, v3
	v_cndmask_b32_e64 v2, 0, v198, s[0:1]
	v_cndmask_b32_e64 v3, 0, v200, s[0:1]
	v_cvt_pk_bf16_f32 v84, v2, v3
	v_cndmask_b32_e64 v2, 0, v136, s[0:1]
	v_cndmask_b32_e64 v3, 0, v184, s[0:1]
	v_cvt_pk_bf16_f32 v88, v2, v3
	v_cndmask_b32_e64 v2, 0, v126, s[0:1]
	v_cndmask_b32_e64 v3, 0, v138, s[0:1]
	v_cvt_pk_bf16_f32 v92, v2, v3
	v_cndmask_b32_e64 v2, 0, v116, s[0:1]
	v_cndmask_b32_e64 v3, 0, v122, s[0:1]
	v_cndmask_b32_e64 v4, 0, -v194, s[0:1]
	v_cndmask_b32_e64 v5, 0, -v196, s[0:1]
	v_cndmask_b32_e64 v6, 0, v191, s[0:1]
	v_cndmask_b32_e64 v7, 0, v193, s[0:1]
	v_cndmask_b32_e64 v8, 0, -v195, s[0:1]
	v_cndmask_b32_e64 v9, 0, -v197, s[0:1]
	v_cvt_pk_bf16_f32 v96, v2, v3
	v_cndmask_b32_e64 v2, 0, v120, s[0:1]
	v_cndmask_b32_e64 v3, 0, v174, s[0:1]
	v_cvt_pk_bf16_f32 v81, v4, v5
	v_cvt_pk_bf16_f32 v82, v6, v7
	v_cvt_pk_bf16_f32 v83, v8, v9
	v_cndmask_b32_e64 v4, 0, -v202, s[0:1]
	v_cndmask_b32_e64 v5, 0, -v204, s[0:1]
	v_cndmask_b32_e64 v6, 0, v199, s[0:1]
	v_cndmask_b32_e64 v7, 0, v201, s[0:1]
	v_cndmask_b32_e64 v8, 0, -v203, s[0:1]
	v_cndmask_b32_e64 v9, 0, -v205, s[0:1]
	v_cvt_pk_bf16_f32 v100, v2, v3
	v_cndmask_b32_e64 v2, 0, v112, s[0:1]
	v_cndmask_b32_e64 v3, 0, v124, s[0:1]
	v_cvt_pk_bf16_f32 v85, v4, v5
	v_cvt_pk_bf16_f32 v86, v6, v7
	v_cvt_pk_bf16_f32 v87, v8, v9
	s_mulk_i32 s46, 0x2200
	v_cndmask_b32_e64 v4, 0, -v186, s[0:1]
	v_cndmask_b32_e64 v5, 0, -v188, s[0:1]
	v_cndmask_b32_e64 v6, 0, v137, s[0:1]
	v_cndmask_b32_e64 v7, 0, v185, s[0:1]
	v_cndmask_b32_e64 v8, 0, -v187, s[0:1]
	v_cndmask_b32_e64 v9, 0, -v189, s[0:1]
	v_cvt_pk_bf16_f32 v104, v2, v3
	v_cndmask_b32_e64 v2, 0, v108, s[0:1]
	v_cndmask_b32_e64 v3, 0, v110, s[0:1]
	v_cvt_pk_bf16_f32 v89, v4, v5
	v_cvt_pk_bf16_f32 v90, v6, v7
	v_cvt_pk_bf16_f32 v91, v8, v9
	v_cndmask_b32_e64 v4, 0, -v176, s[0:1]
	v_cndmask_b32_e64 v5, 0, -v180, s[0:1]
	v_cndmask_b32_e64 v6, 0, v127, s[0:1]
	v_cndmask_b32_e64 v7, 0, v139, s[0:1]
	v_cndmask_b32_e64 v8, 0, -v177, s[0:1]
	v_cndmask_b32_e64 v9, 0, -v181, s[0:1]
	v_cvt_pk_bf16_f32 v108, v2, v3
	s_add_i32 s30, s46, 0
	v_mov_b32_e32 v3, s7
	v_or_b32_e32 v2, s6, v152
	v_cvt_pk_bf16_f32 v93, v4, v5
	v_cvt_pk_bf16_f32 v94, v6, v7
	v_cvt_pk_bf16_f32 v95, v8, v9
	v_cndmask_b32_e64 v4, 0, -v128, s[0:1]
	v_cndmask_b32_e64 v5, 0, -v132, s[0:1]
	v_cndmask_b32_e64 v6, 0, v117, s[0:1]
	v_cndmask_b32_e64 v7, 0, v123, s[0:1]
	v_cndmask_b32_e64 v8, 0, -v129, s[0:1]
	v_cndmask_b32_e64 v9, 0, -v133, s[0:1]
	s_add_u32 s26, s76, s26
	v_lshl_add_u64 v[2:3], v[2:3], 0, s[20:21]
	v_cvt_pk_bf16_f32 v97, v4, v5
	v_cvt_pk_bf16_f32 v98, v6, v7
	v_cvt_pk_bf16_f32 v99, v8, v9
	v_cndmask_b32_e64 v4, 0, -v178, s[0:1]
	v_cndmask_b32_e64 v5, 0, -v182, s[0:1]
	v_cndmask_b32_e64 v6, 0, v121, s[0:1]
	v_cndmask_b32_e64 v7, 0, v175, s[0:1]
	v_cndmask_b32_e64 v8, 0, -v179, s[0:1]
	v_cndmask_b32_e64 v9, 0, -v183, s[0:1]
	s_addc_u32 s27, s77, s27
	v_lshlrev_b64 v[2:3], 6, v[2:3]
	v_cvt_pk_bf16_f32 v101, v4, v5
	v_cvt_pk_bf16_f32 v102, v6, v7
	v_cvt_pk_bf16_f32 v103, v8, v9
	v_cndmask_b32_e64 v4, 0, -v130, s[0:1]
	v_cndmask_b32_e64 v5, 0, -v134, s[0:1]
	v_cndmask_b32_e64 v6, 0, v113, s[0:1]
	v_cndmask_b32_e64 v7, 0, v125, s[0:1]
	v_cndmask_b32_e64 v8, 0, -v131, s[0:1]
	v_cndmask_b32_e64 v9, 0, -v135, s[0:1]
	v_lshl_add_u64 v[2:3], s[26:27], 0, v[2:3]
	v_lshlrev_b32_e32 v142, 2, v150
	v_cvt_pk_bf16_f32 v105, v4, v5
	v_cvt_pk_bf16_f32 v106, v6, v7
	v_cvt_pk_bf16_f32 v107, v8, v9
	v_cndmask_b32_e64 v4, 0, -v114, s[0:1]
	v_cndmask_b32_e64 v5, 0, -v118, s[0:1]
	v_cndmask_b32_e64 v6, 0, v109, s[0:1]
	v_cndmask_b32_e64 v7, 0, v111, s[0:1]
	v_cndmask_b32_e64 v8, 0, -v115, s[0:1]
	v_cndmask_b32_e64 v9, 0, -v119, s[0:1]
	v_lshl_add_u64 v[174:175], v[2:3], 0, v[142:143]
	v_add_u32_e32 v2, s30, v218
	v_cvt_pk_bf16_f32 v109, v4, v5
	v_cvt_pk_bf16_f32 v110, v6, v7
	v_cvt_pk_bf16_f32 v111, v8, v9
	v_add3_u32 v167, s30, v213, v217
	s_mov_b32 s20, 0
	s_mov_b64 s[6:7], -1
	v_add_u32_e32 v180, v2, v210
	s_waitcnt vmcnt(2)
	v_mov_b32_e32 v112, v207
	s_waitcnt vmcnt(0)
	v_mov_b32_e32 v113, v1
	v_mov_b32_e32 v207, v0
	s_branch .LBB0_828
	s_nop 0
	s_nop 0
	s_nop 0
	s_nop 0
	s_nop 0

.LBB0_857:
	s_waitcnt vmcnt(0)
	v_mul_f32_e32 v68, 0x3fb8aa3b, v70
	v_exp_f32_e32 v73, v68
	v_or_b32_e32 v68, s47, v180
	v_lshlrev_b32_e32 v112, 8, v68
	s_lshr_b32 s22, s22, 6
	v_mul_f32_e32 v69, v73, v67
	v_mul_f32_e32 v70, 0.15915494, v69
	v_rndne_f32_e32 v70, v70
	v_fmac_f32_e32 v69, 0xc0c90fdb, v70
	v_fmac_f32_e32 v69, 0x343bbd2e, v70
	v_pk_mul_f32 v[70:71], v[66:67], v[66:67]
	v_mul_f32_e32 v69, 0.15915494, v69
	v_add_f32_e32 v74, v70, v71
	v_div_scale_f32 v71, s[40:41], v74, v74, 1.0
	v_rcp_f32_e32 v75, v71
	v_sin_f32_e32 v70, v69
	v_cos_f32_e32 v72, v69
	v_mul_f32_e32 v68, v66, v73
	v_fma_f32 v69, -v71, v75, 1.0
	v_fmac_f32_e32 v75, v69, v75
	v_div_scale_f32 v69, vcc, 1.0, v74, 1.0
	v_mul_f32_e32 v76, v69, v75
	v_fma_f32 v77, -v71, v76, v69
	v_fmac_f32_e32 v76, v77, v75
	v_fma_f32 v71, -v71, v76, v69
	v_mul_f32_e32 v69, v73, v64
	v_mul_f32_e32 v73, v73, v65
	v_mul_f32_e32 v77, 0.15915494, v73
	v_rndne_f32_e32 v77, v77
	v_fmac_f32_e32 v73, 0xc0c90fdb, v77
	v_fmac_f32_e32 v73, 0x343bbd2e, v77
	v_mul_f32_e32 v68, 0x3fb8aa3b, v68
	v_mul_f32_e32 v69, 0x3fb8aa3b, v69
	v_mul_f32_e32 v77, 0.15915494, v73
	v_exp_f32_e32 v68, v68
	v_exp_f32_e32 v69, v69
	v_cos_f32_e32 v73, v77
	v_div_fmas_f32 v75, v71, v75, v76
	v_sin_f32_e32 v71, v77
	v_div_fixup_f32 v74, v75, v74, 1.0
	v_pk_mul_f32 v[168:169], v[68:69], v[72:73]
	v_ashrrev_i32_e32 v113, 31, v112
	v_pk_mul_f32 v[170:171], v[68:69], v[70:71]
	v_add_f32_e32 v73, -1.0, v168
	v_mov_b32_e32 v68, v67
	v_mov_b32_e32 v69, v66
	v_mov_b32_e32 v72, v170
	v_pk_mul_f32 v[68:69], v[68:69], v[72:73]
	v_pk_mul_f32 v[70:71], v[64:65], v[64:65]
	v_add_f32_e32 v68, v68, v69
	v_add_f32_e32 v69, v70, v71
	v_div_scale_f32 v71, s[40:41], v69, v69, 1.0
	v_rcp_f32_e32 v75, v71
	v_pk_mul_f32 v[66:67], v[66:67], v[72:73]
	v_mov_b32_e32 v73, v64
	v_sub_f32_e32 v66, v66, v67
	v_mul_f32_e32 v70, v74, v66
	v_fma_f32 v66, -v71, v75, 1.0
	v_fmac_f32_e32 v75, v66, v75
	v_div_scale_f32 v66, vcc, 1.0, v69, 1.0
	v_mul_f32_e32 v67, v66, v75
	v_fma_f32 v72, -v71, v67, v66
	v_fmac_f32_e32 v67, v72, v75
	v_fma_f32 v66, -v71, v67, v66
	v_div_fmas_f32 v66, v66, v75, v67
	v_div_fixup_f32 v69, v66, v69, 1.0
	v_add_f32_e32 v67, -1.0, v169
	v_mov_b32_e32 v72, v65
	v_mov_b32_e32 v66, v171
	v_pk_mul_f32 v[72:73], v[72:73], v[66:67]
	v_pk_mul_f32 v[64:65], v[64:65], v[66:67]
	v_add_f32_e32 v71, v72, v73
	v_sub_f32_e32 v64, v64, v65
	v_mul_f32_e32 v68, v74, v68
	v_mul_f32_e32 v78, v69, v64
	v_pk_mul_f32 v[64:65], v[28:29], v[70:71] op_sel_hi:[1,0]
	v_mul_f32_e32 v76, v69, v71
	v_pk_fma_f32 v[64:65], v[24:25], v[68:69], v[64:65] op_sel_hi:[1,0,1] neg_lo:[0,0,1] neg_hi:[0,0,1]
	v_pk_mul_f32 v[24:25], v[24:25], v[70:71] op_sel_hi:[1,0]
	v_cvt_pk_bf16_f32 v64, v64, v65
	v_pk_fma_f32 v[24:25], v[28:29], v[68:69], v[24:25] op_sel_hi:[1,0,1]
	v_pk_mul_f32 v[28:29], v[30:31], v[70:71] op_sel_hi:[1,0]
	s_mulk_i32 s22, 0x2200
	v_pk_fma_f32 v[28:29], v[26:27], v[68:69], v[28:29] op_sel_hi:[1,0,1] neg_lo:[0,0,1] neg_hi:[0,0,1]
	s_add_i32 s25, s22, 0
	v_cvt_pk_bf16_f32 v65, v28, v29
	v_pk_mul_f32 v[28:29], v[30:31], v[68:69] op_sel_hi:[1,0]
	s_lshl_b32 s49, s46, 4
	v_pk_fma_f32 v[26:27], v[26:27], v[70:71], v[28:29] op_sel_hi:[1,0,1]
	v_pk_mul_f32 v[28:29], v[70:71], v[20:21] op_sel_hi:[0,1]
	v_pk_mul_f32 v[20:21], v[68:69], v[20:21] op_sel_hi:[0,1]
	v_pk_fma_f32 v[28:29], v[68:69], v[16:17], v[28:29] op_sel_hi:[0,1,1] neg_lo:[0,0,1] neg_hi:[0,0,1]
	v_pk_fma_f32 v[16:17], v[70:71], v[16:17], v[20:21] op_sel_hi:[0,1,1]
	v_pk_mul_f32 v[20:21], v[70:71], v[22:23] op_sel_hi:[0,1]
	v_pk_fma_f32 v[20:21], v[68:69], v[18:19], v[20:21] op_sel_hi:[0,1,1] neg_lo:[0,0,1] neg_hi:[0,0,1]
	v_cvt_pk_bf16_f32 v67, v20, v21
	v_pk_mul_f32 v[20:21], v[68:69], v[22:23] op_sel_hi:[0,1]
	v_pk_fma_f32 v[18:19], v[70:71], v[18:19], v[20:21] op_sel_hi:[0,1,1]
	v_cvt_pk_bf16_f32 v70, v16, v17
	v_pk_mul_f32 v[16:17], v[78:79], v[12:13] op_sel_hi:[0,1]
	v_pk_mul_f32 v[12:13], v[76:77], v[12:13] op_sel_hi:[0,1]
	v_pk_fma_f32 v[16:17], v[76:77], v[8:9], v[16:17] op_sel_hi:[0,1,1] neg_lo:[0,0,1] neg_hi:[0,0,1]
	v_pk_fma_f32 v[8:9], v[78:79], v[8:9], v[12:13] op_sel_hi:[0,1,1]
	v_pk_mul_f32 v[12:13], v[78:79], v[14:15] op_sel_hi:[0,1]
	v_pk_fma_f32 v[12:13], v[76:77], v[10:11], v[12:13] op_sel_hi:[0,1,1] neg_lo:[0,0,1] neg_hi:[0,0,1]
	v_cvt_pk_bf16_f32 v73, v12, v13
	v_pk_mul_f32 v[12:13], v[76:77], v[14:15] op_sel_hi:[0,1]
	v_pk_fma_f32 v[10:11], v[78:79], v[10:11], v[12:13] op_sel_hi:[0,1,1]
	v_pk_mul_f32 v[12:13], v[78:79], v[4:5] op_sel_hi:[0,1]
	v_pk_mul_f32 v[4:5], v[76:77], v[4:5] op_sel_hi:[0,1]
	v_pk_fma_f32 v[12:13], v[76:77], v[0:1], v[12:13] op_sel_hi:[0,1,1] neg_lo:[0,0,1] neg_hi:[0,0,1]
	v_pk_fma_f32 v[0:1], v[78:79], v[0:1], v[4:5] op_sel_hi:[0,1,1]
	v_pk_mul_f32 v[4:5], v[78:79], v[6:7] op_sel_hi:[0,1]
	v_pk_fma_f32 v[4:5], v[76:77], v[2:3], v[4:5] op_sel_hi:[0,1,1] neg_lo:[0,0,1] neg_hi:[0,0,1]
	v_cvt_pk_bf16_f32 v75, v4, v5
	v_pk_mul_f32 v[4:5], v[76:77], v[6:7] op_sel_hi:[0,1]
	v_pk_fma_f32 v[2:3], v[78:79], v[2:3], v[4:5] op_sel_hi:[0,1,1]
	v_cvt_pk_bf16_f32 v78, v0, v1
	v_cndmask_b32_e64 v0, 0, v80, s[0:1]
	v_cndmask_b32_e64 v1, 0, v82, s[0:1]
	v_cvt_pk_bf16_f32 v79, v2, v3
	v_cndmask_b32_e64 v2, 0, -v110, s[0:1]
	v_cndmask_b32_e64 v3, 0, -v114, s[0:1]
	v_cvt_pk_bf16_f32 v80, v0, v1
	v_cndmask_b32_e64 v0, 0, v84, s[0:1]
	v_cndmask_b32_e64 v1, 0, v86, s[0:1]
	v_cndmask_b32_e64 v4, 0, v81, s[0:1]
	v_cndmask_b32_e64 v5, 0, v83, s[0:1]
	v_cvt_pk_bf16_f32 v81, v2, v3
	v_cndmask_b32_e64 v2, 0, -v106, s[0:1]
	v_cndmask_b32_e64 v3, 0, -v108, s[0:1]
	v_cvt_pk_bf16_f32 v84, v0, v1
	v_cndmask_b32_e64 v0, 0, v88, s[0:1]
	v_cndmask_b32_e64 v1, 0, v90, s[0:1]
	v_cndmask_b32_e64 v6, 0, -v111, s[0:1]
	v_cndmask_b32_e64 v7, 0, -v115, s[0:1]
	v_cvt_pk_bf16_f32 v82, v4, v5
	v_cndmask_b32_e64 v4, 0, v85, s[0:1]
	v_cndmask_b32_e64 v5, 0, v87, s[0:1]
	v_cvt_pk_bf16_f32 v85, v2, v3
	v_cndmask_b32_e64 v2, 0, -v102, s[0:1]
	v_cndmask_b32_e64 v3, 0, -v104, s[0:1]
	v_cvt_pk_bf16_f32 v88, v0, v1
	v_cndmask_b32_e64 v0, 0, v58, s[0:1]
	v_cndmask_b32_e64 v1, 0, v62, s[0:1]
	v_cvt_pk_bf16_f32 v83, v6, v7
	v_cndmask_b32_e64 v6, 0, -v107, s[0:1]
	v_cndmask_b32_e64 v7, 0, -v109, s[0:1]
	v_cvt_pk_bf16_f32 v86, v4, v5
	v_cndmask_b32_e64 v4, 0, v89, s[0:1]
	v_cvt_pk_bf16_f32 v89, v2, v3
	v_cndmask_b32_e64 v2, 0, -v92, s[0:1]
	v_cvt_pk_bf16_f32 v92, v0, v1
	v_cndmask_b32_e64 v0, 0, v54, s[0:1]
	v_cndmask_b32_e64 v1, 0, v96, s[0:1]
	v_cvt_pk_bf16_f32 v87, v6, v7
	v_cndmask_b32_e64 v6, 0, -v103, s[0:1]
	v_cndmask_b32_e64 v7, 0, -v105, s[0:1]
	v_cndmask_b32_e64 v3, 0, -v94, s[0:1]
	v_cvt_pk_bf16_f32 v96, v0, v1
	v_cndmask_b32_e64 v0, 0, v48, s[0:1]
	v_cndmask_b32_e64 v1, 0, v52, s[0:1]
	v_cndmask_b32_e64 v5, 0, v91, s[0:1]
	v_cvt_pk_bf16_f32 v91, v6, v7
	v_cndmask_b32_e64 v6, 0, -v93, s[0:1]
	v_cvt_pk_bf16_f32 v93, v2, v3
	v_cndmask_b32_e64 v3, 0, -v100, s[0:1]
	v_cvt_pk_bf16_f32 v100, v0, v1
	v_cndmask_b32_e64 v0, 0, v42, s[0:1]
	v_cndmask_b32_e64 v1, 0, v44, s[0:1]
	v_cvt_pk_bf16_f32 v104, v0, v1
	v_cndmask_b32_e64 v0, 0, v32, s[0:1]
	v_cndmask_b32_e64 v1, 0, v34, s[0:1]
	v_cvt_pk_bf16_f32 v108, v0, v1
	v_lshlrev_b64 v[0:1], 11, v[112:113]
	v_cvt_pk_bf16_f32 v90, v4, v5
	v_cndmask_b32_e64 v4, 0, v59, s[0:1]
	v_cndmask_b32_e64 v5, 0, v63, s[0:1]
	v_cndmask_b32_e64 v7, 0, -v95, s[0:1]
	v_lshl_add_u64 v[0:1], s[6:7], 0, v[0:1]
	s_lshl_b32 s22, s46, 5
	v_cvt_pk_bf16_f32 v94, v4, v5
	v_cvt_pk_bf16_f32 v95, v6, v7
	v_cndmask_b32_e64 v2, 0, -v98, s[0:1]
	v_cndmask_b32_e64 v4, 0, v55, s[0:1]
	v_cndmask_b32_e64 v5, 0, v97, s[0:1]
	v_cndmask_b32_e64 v6, 0, -v99, s[0:1]
	v_cndmask_b32_e64 v7, 0, -v101, s[0:1]
	v_lshl_add_u64 v[0:1], v[0:1], 0, s[22:23]
	v_mov_b32_e32 v165, v143
	s_add_u32 s26, s76, s26
	v_cvt_pk_bf16_f32 v97, v2, v3
	v_cvt_pk_bf16_f32 v98, v4, v5
	v_cvt_pk_bf16_f32 v99, v6, v7
	v_cndmask_b32_e64 v2, 0, -v56, s[0:1]
	v_cndmask_b32_e64 v3, 0, -v60, s[0:1]
	v_cndmask_b32_e64 v4, 0, v49, s[0:1]
	v_cndmask_b32_e64 v5, 0, v53, s[0:1]
	v_cndmask_b32_e64 v6, 0, -v57, s[0:1]
	v_cndmask_b32_e64 v7, 0, -v61, s[0:1]
	v_lshl_add_u64 v[172:173], v[0:1], 0, v[164:165]
	s_addc_u32 s27, s77, s27
	v_lshlrev_b64 v[0:1], 6, v[36:37]
	v_cvt_pk_bf16_f32 v101, v2, v3
	v_cvt_pk_bf16_f32 v102, v4, v5
	v_cvt_pk_bf16_f32 v103, v6, v7
	v_cndmask_b32_e64 v2, 0, -v46, s[0:1]
	v_cndmask_b32_e64 v3, 0, -v50, s[0:1]
	v_cndmask_b32_e64 v4, 0, v43, s[0:1]
	v_cndmask_b32_e64 v5, 0, v45, s[0:1]
	v_cndmask_b32_e64 v6, 0, -v47, s[0:1]
	v_cndmask_b32_e64 v7, 0, -v51, s[0:1]
	v_lshl_add_u64 v[0:1], s[26:27], 0, v[0:1]
	v_mov_b32_e32 v167, v143
	v_cvt_pk_bf16_f32 v105, v2, v3
	v_cvt_pk_bf16_f32 v106, v4, v5
	v_cvt_pk_bf16_f32 v107, v6, v7
	v_cndmask_b32_e64 v2, 0, -v38, s[0:1]
	v_cndmask_b32_e64 v3, 0, -v40, s[0:1]
	v_cndmask_b32_e64 v4, 0, v33, s[0:1]
	v_cndmask_b32_e64 v5, 0, v35, s[0:1]
	v_cndmask_b32_e64 v6, 0, -v39, s[0:1]
	v_cndmask_b32_e64 v7, 0, -v41, s[0:1]
	v_lshl_add_u64 v[174:175], v[0:1], 0, v[166:167]
	v_add_u32_e32 v0, s25, v184
	v_mov_b32_e32 v112, 0
	v_cvt_pk_bf16_f32 v66, v28, v29
	v_cvt_pk_bf16_f32 v68, v24, v25
	v_cvt_pk_bf16_f32 v69, v26, v27
	v_cvt_pk_bf16_f32 v71, v18, v19
	v_cvt_pk_bf16_f32 v72, v16, v17
	v_cvt_pk_bf16_f32 v74, v12, v13
	v_cvt_pk_bf16_f32 v76, v8, v9
	v_cvt_pk_bf16_f32 v77, v10, v11
	s_mov_b32 s50, 0
	v_cvt_pk_bf16_f32 v109, v2, v3
	v_cvt_pk_bf16_f32 v110, v4, v5
	v_cvt_pk_bf16_f32 v111, v6, v7
	v_add3_u32 v165, s25, v182, v183
	s_mov_b64 s[40:41], -1
	v_add_u32_e32 v167, v0, v185
	v_mov_b32_e32 v113, v112
	v_mov_b32_e32 v114, v112
	v_mov_b32_e32 v115, v112
	s_branch .LBB0_859
	s_nop 0
	s_nop 0
	s_nop 0
	s_nop 0
	s_nop 0
	s_nop 0
	s_nop 0
	s_nop 0
	s_nop 0
	s_nop 0
	s_nop 0
	s_nop 0
	s_nop 0
	s_nop 0

.LBB0_895:
	s_lshr_b32 s6, s42, 6
	s_lshl_b32 s6, s6, 8
	s_add_i32 s6, s6, 0
	v_mov_b32_e32 v15, 0
	s_andn2_b64 vcc, exec, s[20:21]
	v_lshl_add_u32 v186, v146, 2, s6
	v_mov_b32_e32 v14, 0
	v_mov_b32_e32 v13, 0
	v_mov_b32_e32 v12, 0
	v_mov_b32_e32 v11, 0
	v_mov_b32_e32 v10, 0
	v_mov_b32_e32 v9, 0
	v_mov_b32_e32 v8, 0
	v_mov_b32_e32 v7, 0
	v_mov_b32_e32 v6, 0
	v_mov_b32_e32 v5, 0
	v_mov_b32_e32 v4, 0
	v_mov_b32_e32 v3, 0
	v_mov_b32_e32 v2, 0
	v_mov_b32_e32 v1, 0
	v_mov_b32_e32 v0, 0
	v_mov_b32_e32 v31, 0
	v_mov_b32_e32 v30, 0
	v_mov_b32_e32 v29, 0
	v_mov_b32_e32 v28, 0
	v_mov_b32_e32 v27, 0
	v_mov_b32_e32 v26, 0
	v_mov_b32_e32 v25, 0
	v_mov_b32_e32 v24, 0
	v_mov_b32_e32 v23, 0
	v_mov_b32_e32 v22, 0
	v_mov_b32_e32 v21, 0
	v_mov_b32_e32 v20, 0
	v_mov_b32_e32 v19, 0
	v_mov_b32_e32 v18, 0
	v_mov_b32_e32 v17, 0
	v_mov_b32_e32 v16, 0
	v_mov_b32_e32 v63, 0
	v_mov_b32_e32 v62, 0
	v_mov_b32_e32 v61, 0
	v_mov_b32_e32 v60, 0
	v_mov_b32_e32 v59, 0
	v_mov_b32_e32 v58, 0
	v_mov_b32_e32 v57, 0
	v_mov_b32_e32 v56, 0
	v_mov_b32_e32 v55, 0
	v_mov_b32_e32 v54, 0
	v_mov_b32_e32 v53, 0
	v_mov_b32_e32 v52, 0
	v_mov_b32_e32 v51, 0
	v_mov_b32_e32 v50, 0
	v_mov_b32_e32 v49, 0
	v_mov_b32_e32 v48, 0
	v_mov_b32_e32 v47, 0
	v_mov_b32_e32 v46, 0
	v_mov_b32_e32 v45, 0
	v_mov_b32_e32 v44, 0
	v_mov_b32_e32 v43, 0
	v_mov_b32_e32 v42, 0
	v_mov_b32_e32 v41, 0
	v_mov_b32_e32 v40, 0
	v_mov_b32_e32 v39, 0
	v_mov_b32_e32 v38, 0
	v_mov_b32_e32 v37, 0
	v_mov_b32_e32 v36, 0
	v_mov_b32_e32 v35, 0
	v_mov_b32_e32 v34, 0
	v_mov_b32_e32 v33, 0
	v_mov_b32_e32 v32, 0
	v_mov_b32_e32 v64, v145
	v_mov_b32_e32 v188, v184
	s_cbranch_vccnz .LBB0_914
	s_and_b64 s[20:21], s[14:15], exec
	s_cselect_b32 s42, s40, 4
	s_cselect_b32 s50, s19, 0
	s_ashr_i32 s19, s18, 31
	s_lshl_b32 s51, s43, 7
	s_cmp_lt_i32 s42, 1
	s_cselect_b64 s[20:21], -1, 0
	s_and_b64 s[20:21], s[14:15], s[20:21]
	s_and_b64 s[48:49], s[20:21], exec
	s_cselect_b32 s49, s30, s26
	s_cselect_b32 s48, s29, s25
	s_lshl_b32 s43, s43, 8
	s_lshl_b64 s[18:19], s[18:19], 9
	s_or_b32 s18, s18, s43
	s_add_u32 s48, s48, s18
	s_addc_u32 s49, s49, s19
	s_and_b64 s[20:21], s[20:21], exec
	v_lshlrev_b32_e32 v148, 1, v152
	s_cselect_b32 s21, s27, s23
	v_lshl_add_u64 v[0:1], s[48:49], 0, v[148:149]
	v_mov_b32_e32 v157, v149
	s_cselect_b32 s20, s28, s24
	s_add_u32 s18, s21, s18
	v_lshlrev_b32_e32 v158, 1, v150
	v_mov_b32_e32 v159, v149
	v_lshl_add_u64 v[2:3], v[0:1], 0, v[156:157]
	s_addc_u32 s19, s20, s19
	v_lshl_add_u64 v[0:1], v[0:1], 0, v[158:159]
	global_load_dwordx4 v[128:131], v[2:3], off
	global_load_dwordx4 v[132:135], v[0:1], off
	v_lshl_add_u64 v[2:3], s[18:19], 0, v[148:149]
	v_lshl_add_u64 v[4:5], v[2:3], 0, v[156:157]
	v_lshl_add_u64 v[0:1], v[2:3], 0, v[158:159]
	global_load_dwordx4 v[140:143], v[4:5], off
	global_load_dwordx4 v[136:139], v[0:1], off
	v_mbcnt_hi_u32_b32 v188, -1, v183
	v_and_b32_e32 v0, 64, v188
	v_xor_b32_e32 v157, 32, v188
	v_add_u32_e32 v187, 64, v0
	v_cmp_lt_i32_e32 vcc, v157, v187
	s_lshl_b32 s18, s44, 8
	v_mov_b32_e32 v32, v149
	v_cndmask_b32_e32 v0, v188, v157, vcc
	v_lshlrev_b32_e32 v189, 2, v0
	v_add_u32_e32 v0, s50, v176
	v_subrev_u32_e32 v0, s47, v0
	s_add_i32 s47, s47, s46
	v_subrev_u32_e32 v190, s46, v0
	v_add_u32_e32 v0, s47, v177
	v_mov_b32_e32 v33, v149
	v_mov_b32_e32 v46, v149
	v_mov_b32_e32 v47, v149
	s_sub_i32 s45, s18, s45
	v_subrev_u32_e32 v191, s50, v0
	v_mov_b32_e32 v34, v149
	v_mov_b32_e32 v35, v149
	v_mov_b32_e32 v36, v149
	v_mov_b32_e32 v37, v149
	v_mov_b32_e32 v38, v149
	v_mov_b32_e32 v39, v149
	v_mov_b32_e32 v40, v149
	v_mov_b32_e32 v41, v149
	v_mov_b32_e32 v42, v149
	v_mov_b32_e32 v43, v149
	v_mov_b32_e32 v44, v149
	v_mov_b32_e32 v45, v149
	v_mov_b64_e32 v[62:63], v[46:47]
	v_mov_b64_e32 v[16:17], v[32:33]
	v_mov_b64_e32 v[0:1], v[32:33]
	s_waitcnt vmcnt(0)
	v_mul_f32_e32 v193, 0x3fb8aa3b, v65
	s_mov_b32 s43, 0
	s_add_i32 s44, s50, s39
	s_add_i32 s45, s45, 64
	s_lshl_b32 s46, s51, 1
	v_mov_b64_e32 v[60:61], v[44:45]
	v_mov_b64_e32 v[58:59], v[42:43]
	v_mov_b64_e32 v[56:57], v[40:41]
	v_mov_b64_e32 v[54:55], v[38:39]
	v_mov_b64_e32 v[52:53], v[36:37]
	v_mov_b64_e32 v[50:51], v[34:35]
	v_mov_b64_e32 v[48:49], v[32:33]
	v_mov_b64_e32 v[18:19], v[34:35]
	v_mov_b64_e32 v[20:21], v[36:37]
	v_mov_b64_e32 v[22:23], v[38:39]
	v_mov_b64_e32 v[24:25], v[40:41]
	v_mov_b64_e32 v[26:27], v[42:43]
	v_mov_b64_e32 v[28:29], v[44:45]
	v_mov_b64_e32 v[30:31], v[46:47]
	v_mov_b64_e32 v[2:3], v[34:35]
	v_mov_b64_e32 v[4:5], v[36:37]
	v_mov_b64_e32 v[6:7], v[38:39]
	v_mov_b64_e32 v[8:9], v[40:41]
	v_mov_b64_e32 v[10:11], v[42:43]
	v_mov_b64_e32 v[12:13], v[44:45]
	v_mov_b64_e32 v[14:15], v[46:47]
	v_mov_b32_e32 v192, v145
	s_mov_b32 s48, 0
	s_nop 0
	s_nop 0
	s_nop 0
	s_nop 0
	s_nop 0
	s_nop 0
	s_nop 0
	s_nop 0
	s_nop 0
	s_nop 0
	s_nop 0
	s_nop 0

.LBB0_934:
	s_lshr_b32 s6, s42, 6
	s_lshl_b32 s6, s6, 8
	s_add_i32 s6, s6, 0
	v_mov_b32_e32 v15, 0
	s_andn2_b64 vcc, exec, s[20:21]
	v_lshl_add_u32 v184, v146, 2, s6
	v_mov_b32_e32 v14, 0
	v_mov_b32_e32 v13, 0
	v_mov_b32_e32 v12, 0
	v_mov_b32_e32 v11, 0
	v_mov_b32_e32 v10, 0
	v_mov_b32_e32 v9, 0
	v_mov_b32_e32 v8, 0
	v_mov_b32_e32 v7, 0
	v_mov_b32_e32 v6, 0
	v_mov_b32_e32 v5, 0
	v_mov_b32_e32 v4, 0
	v_mov_b32_e32 v3, 0
	v_mov_b32_e32 v2, 0
	v_mov_b32_e32 v1, 0
	v_mov_b32_e32 v0, 0
	v_mov_b32_e32 v31, 0
	v_mov_b32_e32 v30, 0
	v_mov_b32_e32 v29, 0
	v_mov_b32_e32 v28, 0
	v_mov_b32_e32 v27, 0
	v_mov_b32_e32 v26, 0
	v_mov_b32_e32 v25, 0
	v_mov_b32_e32 v24, 0
	v_mov_b32_e32 v23, 0
	v_mov_b32_e32 v22, 0
	v_mov_b32_e32 v21, 0
	v_mov_b32_e32 v20, 0
	v_mov_b32_e32 v19, 0
	v_mov_b32_e32 v18, 0
	v_mov_b32_e32 v17, 0
	v_mov_b32_e32 v16, 0
	v_mov_b32_e32 v63, 0
	v_mov_b32_e32 v62, 0
	v_mov_b32_e32 v61, 0
	v_mov_b32_e32 v60, 0
	v_mov_b32_e32 v59, 0
	v_mov_b32_e32 v58, 0
	v_mov_b32_e32 v57, 0
	v_mov_b32_e32 v56, 0
	v_mov_b32_e32 v55, 0
	v_mov_b32_e32 v54, 0
	v_mov_b32_e32 v53, 0
	v_mov_b32_e32 v52, 0
	v_mov_b32_e32 v51, 0
	v_mov_b32_e32 v50, 0
	v_mov_b32_e32 v49, 0
	v_mov_b32_e32 v48, 0
	v_mov_b32_e32 v47, 0
	v_mov_b32_e32 v46, 0
	v_mov_b32_e32 v45, 0
	v_mov_b32_e32 v44, 0
	v_mov_b32_e32 v43, 0
	v_mov_b32_e32 v42, 0
	v_mov_b32_e32 v41, 0
	v_mov_b32_e32 v40, 0
	v_mov_b32_e32 v39, 0
	v_mov_b32_e32 v38, 0
	v_mov_b32_e32 v37, 0
	v_mov_b32_e32 v36, 0
	v_mov_b32_e32 v35, 0
	v_mov_b32_e32 v34, 0
	v_mov_b32_e32 v33, 0
	v_mov_b32_e32 v32, 0
	v_mov_b32_e32 v64, v149
	v_mov_b32_e32 v186, v182
	s_cbranch_vccnz .LBB0_953
	s_and_b64 s[20:21], s[14:15], exec
	s_cselect_b32 s42, s40, 4
	s_cselect_b32 s50, s19, 0
	s_ashr_i32 s19, s18, 31
	s_lshl_b32 s51, s43, 7
	s_cmp_lt_i32 s42, 1
	s_cselect_b64 s[20:21], -1, 0
	s_and_b64 s[20:21], s[14:15], s[20:21]
	s_and_b64 s[48:49], s[20:21], exec
	s_cselect_b32 s49, s31, s27
	s_cselect_b32 s48, s30, s26
	s_lshl_b32 s43, s43, 8
	s_lshl_b64 s[18:19], s[18:19], 9
	s_or_b32 s18, s18, s43
	s_add_u32 s48, s48, s18
	s_addc_u32 s49, s49, s19
	s_and_b64 s[20:21], s[20:21], exec
	v_lshlrev_b32_e32 v144, 1, v150
	s_cselect_b32 s21, s28, s24
	v_lshl_add_u64 v[0:1], s[48:49], 0, v[144:145]
	v_mov_b32_e32 v155, v145
	s_cselect_b32 s20, s29, s25
	s_add_u32 s18, s21, s18
	v_lshlrev_b32_e32 v156, 1, v148
	v_mov_b32_e32 v157, v145
	v_lshl_add_u64 v[2:3], v[0:1], 0, v[154:155]
	s_addc_u32 s19, s20, s19
	v_lshl_add_u64 v[0:1], v[0:1], 0, v[156:157]
	global_load_dwordx4 v[128:131], v[2:3], off
	global_load_dwordx4 v[132:135], v[0:1], off
	v_lshl_add_u64 v[2:3], s[18:19], 0, v[144:145]
	v_lshl_add_u64 v[4:5], v[2:3], 0, v[154:155]
	v_lshl_add_u64 v[0:1], v[2:3], 0, v[156:157]
	global_load_dwordx4 v[140:143], v[4:5], off
	global_load_dwordx4 v[136:139], v[0:1], off
	v_mbcnt_hi_u32_b32 v186, -1, v181
	v_and_b32_e32 v0, 64, v186
	v_xor_b32_e32 v155, 32, v186
	v_add_u32_e32 v185, 64, v0
	v_cmp_lt_i32_e32 vcc, v155, v185
	s_lshl_b32 s18, s44, 8
	v_mov_b32_e32 v32, v145
	v_cndmask_b32_e32 v0, v186, v155, vcc
	v_lshlrev_b32_e32 v187, 2, v0
	v_add_u32_e32 v0, s50, v174
	v_subrev_u32_e32 v0, s47, v0
	s_add_i32 s47, s47, s46
	v_subrev_u32_e32 v188, s46, v0
	v_add_u32_e32 v0, s47, v175
	v_mov_b32_e32 v33, v145
	v_mov_b32_e32 v46, v145
	v_mov_b32_e32 v47, v145
	s_sub_i32 s45, s18, s45
	v_subrev_u32_e32 v189, s50, v0
	v_mov_b32_e32 v34, v145
	v_mov_b32_e32 v35, v145
	v_mov_b32_e32 v36, v145
	v_mov_b32_e32 v37, v145
	v_mov_b32_e32 v38, v145
	v_mov_b32_e32 v39, v145
	v_mov_b32_e32 v40, v145
	v_mov_b32_e32 v41, v145
	v_mov_b32_e32 v42, v145
	v_mov_b32_e32 v43, v145
	v_mov_b32_e32 v44, v145
	v_mov_b32_e32 v45, v145
	v_mov_b64_e32 v[62:63], v[46:47]
	v_mov_b64_e32 v[16:17], v[32:33]
	v_mov_b64_e32 v[0:1], v[32:33]
	s_waitcnt vmcnt(0)
	v_mul_f32_e32 v191, 0x3fb8aa3b, v65
	s_mov_b32 s43, 0
	s_add_i32 s44, s50, s39
	s_add_i32 s45, s45, 64
	s_lshl_b32 s46, s51, 1
	v_mov_b64_e32 v[60:61], v[44:45]
	v_mov_b64_e32 v[58:59], v[42:43]
	v_mov_b64_e32 v[56:57], v[40:41]
	v_mov_b64_e32 v[54:55], v[38:39]
	v_mov_b64_e32 v[52:53], v[36:37]
	v_mov_b64_e32 v[50:51], v[34:35]
	v_mov_b64_e32 v[48:49], v[32:33]
	v_mov_b64_e32 v[18:19], v[34:35]
	v_mov_b64_e32 v[20:21], v[36:37]
	v_mov_b64_e32 v[22:23], v[38:39]
	v_mov_b64_e32 v[24:25], v[40:41]
	v_mov_b64_e32 v[26:27], v[42:43]
	v_mov_b64_e32 v[28:29], v[44:45]
	v_mov_b64_e32 v[30:31], v[46:47]
	v_mov_b64_e32 v[2:3], v[34:35]
	v_mov_b64_e32 v[4:5], v[36:37]
	v_mov_b64_e32 v[6:7], v[38:39]
	v_mov_b64_e32 v[8:9], v[40:41]
	v_mov_b64_e32 v[10:11], v[42:43]
	v_mov_b64_e32 v[12:13], v[44:45]
	v_mov_b64_e32 v[14:15], v[46:47]
	v_mov_b32_e32 v190, v149
	s_mov_b32 s48, 0
	s_nop 0
	s_nop 0
	s_nop 0
	s_nop 0
	s_nop 0
	s_nop 0
	s_nop 0

.LBB0_1654:
	s_or_b64 exec, exec, s[50:51]
	s_mov_b32 s16, 0x400001
	s_branch .LBB0_1656
	s_nop 0
	s_nop 0
	s_nop 0
	s_nop 0
	s_nop 0
	s_nop 0
